# cross-row steps of the f32 row sums (adaLN, post-pass, final norm) via v_permlane16_swap/v_permlane32_swap instead of ds_bpermute + lgkmcnt wait
# speedup vs baseline: 1.0013x; 1.0013x over previous
.LBB0_157:
	v_lshlrev_b32_e32 v85, 16, v22
	v_and_b32_e32 v87, 0xffff0000, v22
	v_and_b32_e32 v86, 0xffff0000, v20
	v_lshlrev_b32_e32 v89, 16, v23
	v_and_b32_e32 v23, 0xffff0000, v23
	v_and_b32_e32 v22, 0xffff0000, v21
	v_lshlrev_b32_e32 v84, 16, v20
	v_lshlrev_b32_e32 v88, 16, v21
	v_pk_mul_f32 v[20:21], v[86:87], v[86:87]
	v_pk_mul_f32 v[90:91], v[22:23], v[22:23]
	v_pk_fma_f32 v[20:21], v[84:85], v[84:85], v[20:21]
	v_pk_fma_f32 v[90:91], v[88:89], v[88:89], v[90:91]
	v_lshlrev_b32_e32 v97, 16, v17
	v_pk_add_f32 v[20:21], v[20:21], v[90:91]
	v_lshlrev_b32_e32 v96, 16, v16
	v_and_b32_e32 v17, 0xffff0000, v17
	v_and_b32_e32 v16, 0xffff0000, v16
	v_pk_add_f32 v[20:21], v[20:21], v[20:21] op_sel_hi:[0,1]
	v_lshlrev_b32_e32 v90, 16, v18
	v_and_b32_e32 v91, 0xffff0000, v18
	v_pk_mul_f32 v[98:99], v[16:17], v[16:17]
	v_lshlrev_b32_e32 v18, 16, v19
	v_lshlrev_b32_e32 v100, 16, v12
	v_pk_fma_f32 v[98:99], v[96:97], v[96:97], v[98:99]
	v_mul_f32_e32 v101, v90, v90
	v_mul_f32_e32 v103, v91, v91
	v_and_b32_e32 v19, 0xffff0000, v19
	v_mul_f32_e32 v20, v18, v18
	v_mov_b32_e32 v102, v100
	v_pk_add_f32 v[98:99], v[98:99], v[98:99] op_sel_hi:[0,1]
	v_pk_fma_f32 v[104:105], v[18:19], v[18:19], v[20:21] op_sel_hi:[1,1,0]
	v_and_b32_e32 v114, 0xffff0000, v12
	v_lshlrev_b32_e32 v12, 16, v13
	v_and_b32_e32 v13, 0xffff0000, v13
	v_pk_add_f32 v[102:103], v[100:101], v[102:103]
	v_mul_f32_e32 v104, v114, v114
	v_mul_f32_e32 v20, v12, v12
	v_mul_f32_e32 v98, v13, v13
	v_mul_f32_e32 v106, v100, v100
	v_mov_b32_e32 v107, v103
	v_pk_add_f32 v[102:103], v[106:107], v[104:105]
	v_pk_add_f32 v[20:21], v[20:21], v[98:99]
	v_lshlrev_b32_e32 v99, 16, v15
	v_lshlrev_b32_e32 v98, 16, v14
	v_and_b32_e32 v15, 0xffff0000, v15
	v_and_b32_e32 v14, 0xffff0000, v14
	v_pk_add_f32 v[20:21], v[102:103], v[20:21]
	v_pk_mul_f32 v[102:103], v[14:15], v[14:15]
	v_lshlrev_b32_e32 v104, 16, v8
	v_and_b32_e32 v105, 0xffff0000, v8
	v_lshlrev_b32_e32 v106, 16, v10
	v_lshlrev_b32_e32 v110, 16, v9
	v_pk_fma_f32 v[102:103], v[98:99], v[98:99], v[102:103]
	v_and_b32_e32 v115, 0xffff0000, v10
	v_lshlrev_b32_e32 v108, 16, v11
	v_and_b32_e32 v109, 0xffff0000, v11
	v_mul_f32_e32 v107, v104, v104
	v_mul_f32_e32 v11, v105, v105
	v_and_b32_e32 v111, 0xffff0000, v9
	v_mul_f32_e32 v8, v110, v110
	v_mov_b32_e32 v10, v106
	v_pk_add_f32 v[20:21], v[20:21], v[20:21] op_sel_hi:[0,1]
	v_pk_add_f32 v[102:103], v[102:103], v[102:103] op_sel_hi:[0,1]
	v_pk_fma_f32 v[8:9], v[110:111], v[110:111], v[8:9] op_sel_hi:[1,1,0]
	v_pk_add_f32 v[10:11], v[106:107], v[10:11]
	v_mul_f32_e32 v8, v115, v115
	v_mul_f32_e32 v102, v108, v108
	v_mul_f32_e32 v20, v109, v109
	v_mul_f32_e32 v112, v106, v106
	v_mov_b32_e32 v113, v11
	v_pk_add_f32 v[8:9], v[112:113], v[8:9]
	v_pk_add_f32 v[10:11], v[102:103], v[20:21]
	s_ashr_i32 s17, s16, 31
	v_pk_add_f32 v[8:9], v[8:9], v[10:11]
	v_mov_b32_e32 v101, v114
	v_add_f32_e32 v8, v8, v9
	ds_bpermute_b32 v9, v1, v8
	v_mov_b32_e32 v107, v115
	s_waitcnt lgkmcnt(0)
	v_add_f32_e32 v8, v8, v9
	s_nop 1
	v_add_f32_dpp v8, v8, v8 quad_perm:[2,3,0,1] row_mask:0xf bank_mask:0xf
	s_nop 1
	v_add_f32_dpp v8, v8, v8 row_half_mirror row_mask:0xf bank_mask:0xf
	s_nop 1
	v_add_f32_dpp v8, v8, v8 row_mirror row_mask:0xf bank_mask:0xf
	v_mov_b32_e32 v9, v8
	s_nop 1
	v_permlane16_swap_b32_e32 v8, v9
	v_add_f32_e32 v8, v8, v9
	v_mov_b32_e32 v9, v8
	s_nop 1
	v_permlane32_swap_b32_e32 v8, v9
	s_waitcnt lgkmcnt(0)
	v_add_f32_e32 v8, v8, v9
	v_fmamk_f32 v8, v8, 0x3a000000, v234
	v_mul_f32_e32 v9, 0x4f800000, v8
	v_cmp_gt_f32_e32 vcc, s3, v8
	s_nop 1
	v_cndmask_b32_e32 v8, v8, v9, vcc
	v_sqrt_f32_e32 v9, v8
	s_nop 0
	v_add_u32_e32 v10, -1, v9
	v_fma_f32 v11, -v10, v9, v8
	v_cmp_ge_f32_e64 s[48:49], 0, v11
	v_add_u32_e32 v11, 1, v9
	s_nop 0
	v_cndmask_b32_e64 v10, v9, v10, s[48:49]
	v_fma_f32 v9, -v11, v9, v8
	v_cmp_lt_f32_e64 s[48:49], 0, v9
	s_nop 1
	v_cndmask_b32_e64 v9, v10, v11, s[48:49]
	v_mul_f32_e32 v10, 0x37800000, v9
	v_cndmask_b32_e32 v9, v9, v10, vcc
	v_cmp_class_f32_e32 vcc, v8, v235
	s_nop 1
	v_cndmask_b32_e32 v8, v9, v8, vcc
	v_div_scale_f32 v9, s[12:13], v8, v8, 1.0
	v_rcp_f32_e32 v10, v9
	s_lshl_b64 s[12:13], s[16:17], 12
	v_lshl_add_u64 v[102:103], v[122:123], 0, s[12:13]
	v_fma_f32 v11, -v9, v10, 1.0
	v_fmac_f32_e32 v10, v11, v10
	v_div_scale_f32 v11, vcc, 1.0, v8, 1.0
	v_mul_f32_e32 v20, v11, v10
	v_fma_f32 v21, -v9, v20, v11
	v_fmac_f32_e32 v20, v21, v10
	v_fma_f32 v9, -v9, v20, v11
	v_div_fmas_f32 v9, v9, v10, v20
	v_div_fixup_f32 v20, v9, v8, 1.0
	v_mov_b32_e32 v8, v84
	v_mov_b32_e32 v9, v86
	v_mov_b32_e32 v10, v88
	v_mov_b32_e32 v11, v22
	v_mov_b32_e32 v86, v85
	v_mov_b32_e32 v22, v89
	v_pk_mul_f32 v[8:9], v[20:21], v[8:9] op_sel_hi:[0,1]
	v_pk_mul_f32 v[10:11], v[20:21], v[10:11] op_sel_hi:[0,1]
	v_pk_mul_f32 v[84:85], v[20:21], v[86:87] op_sel_hi:[0,1]
	v_pk_mul_f32 v[22:23], v[20:21], v[22:23] op_sel_hi:[0,1]
	s_waitcnt vmcnt(6)
	v_pk_fma_f32 v[10:11], v[46:47], v[10:11], v[30:31]
	v_pk_fma_f32 v[8:9], v[44:45], v[8:9], v[28:29]
	v_pk_fma_f32 v[22:23], v[54:55], v[22:23], v[26:27]
	v_pk_fma_f32 v[84:85], v[52:53], v[84:85], v[24:25]
	v_cvt_pk_bf16_f32 v8, v8, v9
	v_cvt_pk_bf16_f32 v9, v10, v11
	v_cvt_pk_bf16_f32 v10, v84, v85
	v_cvt_pk_bf16_f32 v11, v22, v23
	global_store_dwordx4 v[102:103], v[8:11], off
	v_pk_mul_f32 v[18:19], v[20:21], v[18:19] op_sel_hi:[0,1]
	s_waitcnt vmcnt(6)
	v_pk_fma_f32 v[18:19], v[62:63], v[18:19], v[34:35]
	v_mov_b32_e32 v8, v96
	v_mov_b32_e32 v9, v16
	v_mov_b32_e32 v16, v97
	v_pk_mul_f32 v[8:9], v[20:21], v[8:9] op_sel_hi:[0,1]
	v_pk_mul_f32 v[10:11], v[20:21], v[16:17] op_sel_hi:[0,1]
	v_pk_mul_f32 v[16:17], v[20:21], v[90:91] op_sel_hi:[0,1]
	s_waitcnt vmcnt(5)
	v_pk_fma_f32 v[10:11], v[58:59], v[10:11], v[38:39]
	v_pk_fma_f32 v[8:9], v[56:57], v[8:9], v[36:37]
	v_pk_fma_f32 v[16:17], v[60:61], v[16:17], v[32:33]
	v_cvt_pk_bf16_f32 v8, v8, v9
	v_cvt_pk_bf16_f32 v9, v10, v11
	v_cvt_pk_bf16_f32 v10, v16, v17
	v_cvt_pk_bf16_f32 v11, v18, v19
	global_store_dwordx4 v[102:103], v[8:11], off offset:1024
	s_nop 1
	v_pk_mul_f32 v[10:11], v[20:21], v[12:13] op_sel_hi:[0,1]
	v_mov_b32_e32 v12, v98
	v_mov_b32_e32 v13, v14
	v_mov_b32_e32 v14, v99
	v_pk_mul_f32 v[8:9], v[20:21], v[100:101] op_sel_hi:[0,1]
	v_pk_mul_f32 v[12:13], v[20:21], v[12:13] op_sel_hi:[0,1]
	v_pk_mul_f32 v[14:15], v[20:21], v[14:15] op_sel_hi:[0,1]
	s_waitcnt vmcnt(4)
	v_pk_fma_f32 v[10:11], v[66:67], v[10:11], v[50:51]
	v_pk_fma_f32 v[8:9], v[64:65], v[8:9], v[48:49]
	v_pk_fma_f32 v[14:15], v[70:71], v[14:15], v[42:43]
	v_pk_fma_f32 v[12:13], v[68:69], v[12:13], v[40:41]
	v_cvt_pk_bf16_f32 v8, v8, v9
	v_cvt_pk_bf16_f32 v9, v10, v11
	v_cvt_pk_bf16_f32 v10, v12, v13
	v_cvt_pk_bf16_f32 v11, v14, v15
	global_store_dwordx4 v[102:103], v[8:11], off offset:2048
	v_pk_mul_f32 v[12:13], v[20:21], v[106:107] op_sel_hi:[0,1]
	v_pk_mul_f32 v[14:15], v[20:21], v[108:109] op_sel_hi:[0,1]
	v_pk_mul_f32 v[8:9], v[20:21], v[104:105] op_sel_hi:[0,1]
	v_pk_mul_f32 v[10:11], v[20:21], v[110:111] op_sel_hi:[0,1]
	s_waitcnt vmcnt(3)
	v_pk_fma_f32 v[10:11], v[82:83], v[10:11], v[78:79]
	v_pk_fma_f32 v[8:9], v[80:81], v[8:9], v[76:77]
	v_pk_fma_f32 v[14:15], v[94:95], v[14:15], v[74:75]
	v_pk_fma_f32 v[12:13], v[92:93], v[12:13], v[72:73]
	v_cvt_pk_bf16_f32 v8, v8, v9
	v_cvt_pk_bf16_f32 v9, v10, v11
	v_cvt_pk_bf16_f32 v10, v12, v13
	v_cvt_pk_bf16_f32 v11, v14, v15
	global_store_dwordx4 v[102:103], v[8:11], off offset:3072

.LBB0_161:
	s_waitcnt vmcnt(0)
	v_lshlrev_b32_e32 v137, 16, v118
	v_and_b32_e32 v139, 0xffff0000, v118
	v_and_b32_e32 v138, 0xffff0000, v116
	v_lshlrev_b32_e32 v141, 16, v119
	v_and_b32_e32 v119, 0xffff0000, v119
	v_and_b32_e32 v118, 0xffff0000, v117
	v_lshlrev_b32_e32 v136, 16, v116
	v_lshlrev_b32_e32 v140, 16, v117
	v_pk_mul_f32 v[116:117], v[138:139], v[138:139]
	v_pk_mul_f32 v[142:143], v[118:119], v[118:119]
	v_pk_fma_f32 v[116:117], v[136:137], v[136:137], v[116:117]
	v_pk_fma_f32 v[142:143], v[140:141], v[140:141], v[142:143]
	s_waitcnt vmcnt(10)
	v_lshlrev_b32_e32 v145, 16, v113
	v_pk_add_f32 v[116:117], v[116:117], v[142:143]
	v_lshlrev_b32_e32 v144, 16, v112
	v_and_b32_e32 v113, 0xffff0000, v113
	v_and_b32_e32 v112, 0xffff0000, v112
	v_pk_add_f32 v[116:117], v[116:117], v[116:117] op_sel_hi:[0,1]
	v_lshlrev_b32_e32 v142, 16, v114
	v_and_b32_e32 v143, 0xffff0000, v114
	v_pk_mul_f32 v[146:147], v[112:113], v[112:113]
	v_lshlrev_b32_e32 v114, 16, v115
	s_waitcnt vmcnt(9)
	v_lshlrev_b32_e32 v148, 16, v108
	v_pk_fma_f32 v[146:147], v[144:145], v[144:145], v[146:147]
	v_mul_f32_e32 v149, v142, v142
	v_mul_f32_e32 v151, v143, v143
	v_and_b32_e32 v115, 0xffff0000, v115
	v_mul_f32_e32 v116, v114, v114
	v_mov_b32_e32 v150, v148
	v_pk_add_f32 v[146:147], v[146:147], v[146:147] op_sel_hi:[0,1]
	v_pk_fma_f32 v[152:153], v[114:115], v[114:115], v[116:117] op_sel_hi:[1,1,0]
	v_and_b32_e32 v135, 0xffff0000, v108
	v_lshlrev_b32_e32 v108, 16, v109
	v_and_b32_e32 v109, 0xffff0000, v109
	v_pk_add_f32 v[150:151], v[148:149], v[150:151]
	v_mul_f32_e32 v152, v135, v135
	v_mul_f32_e32 v116, v108, v108
	v_mul_f32_e32 v146, v109, v109
	v_mul_f32_e32 v154, v148, v148
	v_mov_b32_e32 v155, v151
	v_pk_add_f32 v[150:151], v[154:155], v[152:153]
	v_pk_add_f32 v[116:117], v[116:117], v[146:147]
	v_lshlrev_b32_e32 v147, 16, v111
	v_lshlrev_b32_e32 v146, 16, v110
	v_and_b32_e32 v111, 0xffff0000, v111
	v_and_b32_e32 v110, 0xffff0000, v110
	v_pk_add_f32 v[116:117], v[150:151], v[116:117]
	v_pk_mul_f32 v[150:151], v[110:111], v[110:111]
	s_waitcnt vmcnt(8)
	v_lshlrev_b32_e32 v152, 16, v104
	v_and_b32_e32 v153, 0xffff0000, v104
	v_lshlrev_b32_e32 v154, 16, v106
	v_lshlrev_b32_e32 v158, 16, v105
	v_pk_fma_f32 v[150:151], v[146:147], v[146:147], v[150:151]
	v_and_b32_e32 v162, 0xffff0000, v106
	v_lshlrev_b32_e32 v156, 16, v107
	v_and_b32_e32 v157, 0xffff0000, v107
	v_mul_f32_e32 v155, v152, v152
	v_mul_f32_e32 v107, v153, v153
	v_and_b32_e32 v159, 0xffff0000, v105
	v_mul_f32_e32 v104, v158, v158
	v_mov_b32_e32 v106, v154
	v_pk_add_f32 v[116:117], v[116:117], v[116:117] op_sel_hi:[0,1]
	v_pk_add_f32 v[150:151], v[150:151], v[150:151] op_sel_hi:[0,1]
	v_pk_fma_f32 v[104:105], v[158:159], v[158:159], v[104:105] op_sel_hi:[1,1,0]
	v_pk_add_f32 v[106:107], v[154:155], v[106:107]
	v_mul_f32_e32 v104, v162, v162
	v_mul_f32_e32 v150, v156, v156
	v_mul_f32_e32 v116, v157, v157
	v_mul_f32_e32 v160, v154, v154
	v_mov_b32_e32 v161, v107
	v_pk_add_f32 v[104:105], v[160:161], v[104:105]
	v_pk_add_f32 v[106:107], v[150:151], v[116:117]
	v_lshl_add_u64 v[150:151], s[10:11], 0, v[2:3]
	v_pk_add_f32 v[104:105], v[104:105], v[106:107]
	v_mov_b32_e32 v149, v135
	v_add_f32_e32 v104, v104, v105
	v_mov_b32_e32 v155, v162
	s_cmp_ge_i32 s9, s14
	s_nop 1
	v_add_f32_dpp v104, v104, v104 quad_perm:[1,0,3,2] row_mask:0xf bank_mask:0xf
	s_nop 1
	v_add_f32_dpp v104, v104, v104 quad_perm:[2,3,0,1] row_mask:0xf bank_mask:0xf
	s_nop 1
	v_add_f32_dpp v104, v104, v104 row_half_mirror row_mask:0xf bank_mask:0xf
	s_nop 1
	v_add_f32_dpp v104, v104, v104 row_mirror row_mask:0xf bank_mask:0xf
	v_mov_b32_e32 v105, v104
	s_nop 1
	v_permlane16_swap_b32_e32 v104, v105
	v_add_f32_e32 v104, v104, v105
	v_mov_b32_e32 v105, v104
	s_nop 1
	v_permlane32_swap_b32_e32 v104, v105
	s_waitcnt lgkmcnt(0)
	v_add_f32_e32 v104, v104, v105
	v_fmamk_f32 v104, v104, 0x3a000000, v234
	v_mul_f32_e32 v105, 0x4f800000, v104
	v_cmp_gt_f32_e32 vcc, s3, v104
	s_nop 1
	v_cndmask_b32_e32 v104, v104, v105, vcc
	v_sqrt_f32_e32 v105, v104
	s_nop 0
	v_add_u32_e32 v106, -1, v105
	v_fma_f32 v107, -v106, v105, v104
	v_cmp_ge_f32_e64 s[48:49], 0, v107
	v_add_u32_e32 v107, 1, v105
	s_nop 0
	v_cndmask_b32_e64 v106, v105, v106, s[48:49]
	v_fma_f32 v105, -v107, v105, v104
	v_cmp_lt_f32_e64 s[48:49], 0, v105
	s_nop 1
	v_cndmask_b32_e64 v105, v106, v107, s[48:49]
	v_mul_f32_e32 v106, 0x37800000, v105
	v_cndmask_b32_e32 v105, v105, v106, vcc
	v_cmp_class_f32_e32 vcc, v104, v235
	s_nop 1
	v_cndmask_b32_e32 v104, v105, v104, vcc
	v_div_scale_f32 v105, s[12:13], v104, v104, 1.0
	v_rcp_f32_e32 v106, v105
	s_nop 0
	v_fma_f32 v107, -v105, v106, 1.0
	v_fmac_f32_e32 v106, v107, v106
	v_div_scale_f32 v107, vcc, 1.0, v104, 1.0
	v_mul_f32_e32 v116, v107, v106
	v_fma_f32 v117, -v105, v116, v107
	v_fmac_f32_e32 v116, v117, v106
	v_fma_f32 v105, -v105, v116, v107
	v_div_fmas_f32 v105, v105, v106, v116
	v_div_fixup_f32 v116, v105, v104, 1.0
	v_mov_b32_e32 v104, v136
	v_mov_b32_e32 v105, v138
	v_mov_b32_e32 v106, v140
	v_mov_b32_e32 v107, v118
	v_mov_b32_e32 v118, v141
	v_pk_mul_f32 v[104:105], v[116:117], v[104:105] op_sel_hi:[0,1]
	v_pk_mul_f32 v[106:107], v[116:117], v[106:107] op_sel_hi:[0,1]
	v_mov_b32_e32 v138, v137
	v_pk_mul_f32 v[118:119], v[116:117], v[118:119] op_sel_hi:[0,1]
	s_waitcnt vmcnt(6)
	v_pk_fma_f32 v[106:107], v[46:47], v[106:107], v[30:31]
	v_pk_fma_f32 v[104:105], v[44:45], v[104:105], v[28:29]
	v_pk_mul_f32 v[136:137], v[116:117], v[138:139] op_sel_hi:[0,1]
	v_pk_fma_f32 v[118:119], v[54:55], v[118:119], v[26:27]
	v_pk_fma_f32 v[136:137], v[52:53], v[136:137], v[24:25]
	v_cvt_pk_bf16_f32 v104, v104, v105
	v_cvt_pk_bf16_f32 v105, v106, v107
	v_cvt_pk_bf16_f32 v107, v118, v119
	v_add_co_u32_e32 v118, vcc, s24, v150
	v_cvt_pk_bf16_f32 v106, v136, v137
	s_nop 0
	v_addc_co_u32_e32 v119, vcc, 0, v151, vcc
	global_store_dwordx4 v[118:119], v[104:107], off
	v_pk_mul_f32 v[114:115], v[116:117], v[114:115] op_sel_hi:[0,1]
	s_waitcnt vmcnt(6)
	v_pk_fma_f32 v[114:115], v[62:63], v[114:115], v[34:35]
	v_mov_b32_e32 v104, v144
	v_mov_b32_e32 v105, v112
	v_mov_b32_e32 v112, v145
	v_pk_mul_f32 v[104:105], v[116:117], v[104:105] op_sel_hi:[0,1]
	v_pk_mul_f32 v[106:107], v[116:117], v[112:113] op_sel_hi:[0,1]
	v_pk_mul_f32 v[112:113], v[116:117], v[142:143] op_sel_hi:[0,1]
	s_waitcnt vmcnt(5)
	v_pk_fma_f32 v[106:107], v[58:59], v[106:107], v[38:39]
	v_pk_fma_f32 v[104:105], v[56:57], v[104:105], v[36:37]
	v_pk_fma_f32 v[112:113], v[60:61], v[112:113], v[32:33]
	v_cvt_pk_bf16_f32 v104, v104, v105
	v_cvt_pk_bf16_f32 v105, v106, v107
	v_cvt_pk_bf16_f32 v106, v112, v113
	v_cvt_pk_bf16_f32 v107, v114, v115
	global_store_dwordx4 v[118:119], v[104:107], off offset:1024
	s_nop 1
	v_pk_mul_f32 v[106:107], v[116:117], v[108:109] op_sel_hi:[0,1]
	v_mov_b32_e32 v108, v146
	v_mov_b32_e32 v109, v110
	v_mov_b32_e32 v110, v147
	v_pk_mul_f32 v[104:105], v[116:117], v[148:149] op_sel_hi:[0,1]
	v_pk_mul_f32 v[108:109], v[116:117], v[108:109] op_sel_hi:[0,1]
	v_pk_mul_f32 v[110:111], v[116:117], v[110:111] op_sel_hi:[0,1]
	s_waitcnt vmcnt(4)
	v_pk_fma_f32 v[106:107], v[66:67], v[106:107], v[50:51]
	v_pk_fma_f32 v[104:105], v[64:65], v[104:105], v[48:49]
	v_pk_fma_f32 v[110:111], v[70:71], v[110:111], v[42:43]
	v_pk_fma_f32 v[108:109], v[68:69], v[108:109], v[40:41]
	v_cvt_pk_bf16_f32 v104, v104, v105
	v_cvt_pk_bf16_f32 v105, v106, v107
	v_cvt_pk_bf16_f32 v106, v108, v109
	v_cvt_pk_bf16_f32 v107, v110, v111
	global_store_dwordx4 v[118:119], v[104:107], off offset:2048
	v_pk_mul_f32 v[108:109], v[116:117], v[154:155] op_sel_hi:[0,1]
	v_pk_mul_f32 v[110:111], v[116:117], v[156:157] op_sel_hi:[0,1]
	v_pk_mul_f32 v[104:105], v[116:117], v[152:153] op_sel_hi:[0,1]
	v_pk_mul_f32 v[106:107], v[116:117], v[158:159] op_sel_hi:[0,1]
	s_waitcnt vmcnt(3)
	v_pk_fma_f32 v[106:107], v[82:83], v[106:107], v[78:79]
	v_pk_fma_f32 v[104:105], v[80:81], v[104:105], v[76:77]
	v_pk_fma_f32 v[110:111], v[94:95], v[110:111], v[74:75]
	v_pk_fma_f32 v[108:109], v[92:93], v[108:109], v[72:73]
	v_cvt_pk_bf16_f32 v104, v104, v105
	v_cvt_pk_bf16_f32 v105, v106, v107
	v_cvt_pk_bf16_f32 v106, v108, v109
	v_cvt_pk_bf16_f32 v107, v110, v111
	global_store_dwordx4 v[118:119], v[104:107], off offset:3072
	s_cbranch_scc1 .LBB0_165
	s_add_i32 s9, s8, 0xfffff001
	s_lshr_b32 s9, s9, 10
	s_add_i32 s9, s9, 1
	s_cmpk_gt_i32 s8, 0xffe
	s_cselect_b32 s9, s9, 0
	s_cmp_eq_u32 s9, s20
	s_cbranch_scc1 .LBB0_164
	s_mul_i32 s13, s9, 0x12000
	s_mul_hi_u32 s12, s9, 0x12000
	s_add_u32 s17, s15, s13
	s_addc_u32 s22, s18, s12
	s_lshl_b64 s[12:13], s[42:43], 2
	s_add_u32 s12, s17, s12
	s_addc_u32 s13, s22, s13
	v_lshlrev_b32_e32 v60, 2, v120
	global_load_dwordx4 v[32:35], v[124:125], off offset:16
	global_load_dwordx4 v[24:27], v[124:125], off
	global_load_dwordx4 v[36:39], v60, s[12:13] offset:16
	global_load_dwordx4 v[28:31], v60, s[12:13]
	s_lshl_b64 s[20:21], s[36:37], 2
	s_add_u32 s20, s17, s20
	s_addc_u32 s21, s22, s21
	v_lshlrev_b32_e32 v76, 2, v126
	v_lshlrev_b32_e32 v108, 2, v130
	s_waitcnt vmcnt(1)
	v_pk_add_f32 v[38:39], v[38:39], 1.0 op_sel_hi:[1,0]
	s_waitcnt vmcnt(0)
	v_pk_add_f32 v[30:31], v[30:31], 1.0 op_sel_hi:[1,0]
	v_pk_add_f32 v[28:29], v[28:29], 1.0 op_sel_hi:[1,0]
	v_pk_add_f32 v[36:37], v[36:37], 1.0 op_sel_hi:[1,0]
	v_pk_mul_f32 v[46:47], v[26:27], v[30:31]
	v_pk_mul_f32 v[44:45], v[24:25], v[28:29]
	global_load_dwordx4 v[24:27], v60, s[20:21] offset:16
	global_load_dwordx4 v[28:31], v60, s[20:21]
	v_pk_mul_f32 v[54:55], v[34:35], v[38:39]
	v_pk_mul_f32 v[52:53], v[32:33], v[36:37]
	global_load_dwordx4 v[40:43], v[124:125], off offset:2064
	global_load_dwordx4 v[32:35], v[124:125], off offset:2048
	global_load_dwordx4 v[48:51], v60, s[12:13] offset:2064
	global_load_dwordx4 v[36:39], v60, s[12:13] offset:2048
	s_waitcnt vmcnt(1)
	v_pk_add_f32 v[50:51], v[50:51], 1.0 op_sel_hi:[1,0]
	s_waitcnt vmcnt(0)
	v_pk_add_f32 v[38:39], v[38:39], 1.0 op_sel_hi:[1,0]
	v_pk_add_f32 v[36:37], v[36:37], 1.0 op_sel_hi:[1,0]
	v_pk_add_f32 v[48:49], v[48:49], 1.0 op_sel_hi:[1,0]
	v_pk_mul_f32 v[58:59], v[34:35], v[38:39]
	v_pk_mul_f32 v[56:57], v[32:33], v[36:37]
	global_load_dwordx4 v[32:35], v60, s[20:21] offset:2064
	global_load_dwordx4 v[36:39], v60, s[20:21] offset:2048
	v_pk_mul_f32 v[62:63], v[42:43], v[50:51]
	v_pk_mul_f32 v[60:61], v[40:41], v[48:49]
	global_load_dwordx4 v[68:71], v[128:129], off offset:16
	global_load_dwordx4 v[40:43], v[128:129], off
	global_load_dwordx4 v[72:75], v76, s[12:13] offset:16
	global_load_dwordx4 v[48:51], v76, s[12:13]
	s_waitcnt vmcnt(1)
	v_pk_add_f32 v[74:75], v[74:75], 1.0 op_sel_hi:[1,0]
	s_waitcnt vmcnt(0)
	v_pk_add_f32 v[50:51], v[50:51], 1.0 op_sel_hi:[1,0]
	v_pk_add_f32 v[48:49], v[48:49], 1.0 op_sel_hi:[1,0]
	v_pk_add_f32 v[72:73], v[72:73], 1.0 op_sel_hi:[1,0]
	v_pk_mul_f32 v[66:67], v[42:43], v[50:51]
	v_pk_mul_f32 v[64:65], v[40:41], v[48:49]
	global_load_dwordx4 v[40:43], v76, s[20:21] offset:16
	global_load_dwordx4 v[48:51], v76, s[20:21]
	v_pk_mul_f32 v[70:71], v[70:71], v[74:75]
	v_pk_mul_f32 v[68:69], v[68:69], v[72:73]
	global_load_dwordx4 v[92:95], v[132:133], off offset:16
	global_load_dwordx4 v[72:75], v[132:133], off
	global_load_dwordx4 v[104:107], v108, s[12:13] offset:16
	global_load_dwordx4 v[76:79], v108, s[12:13]
	s_waitcnt vmcnt(1)
	v_pk_add_f32 v[106:107], v[106:107], 1.0 op_sel_hi:[1,0]
	s_waitcnt vmcnt(0)
	v_pk_add_f32 v[78:79], v[78:79], 1.0 op_sel_hi:[1,0]
	v_pk_add_f32 v[76:77], v[76:77], 1.0 op_sel_hi:[1,0]
	v_pk_mul_f32 v[82:83], v[74:75], v[78:79]
	v_pk_mul_f32 v[80:81], v[72:73], v[76:77]
	global_load_dwordx4 v[72:75], v108, s[20:21] offset:16
	global_load_dwordx4 v[76:79], v108, s[20:21]
	v_pk_add_f32 v[104:105], v[104:105], 1.0 op_sel_hi:[1,0]
	v_pk_mul_f32 v[94:95], v[94:95], v[106:107]
	v_pk_mul_f32 v[92:93], v[92:93], v[104:105]
	s_mov_b32 s20, s9
.LBB0_164:
	v_lshlrev_b32_e32 v105, 16, v102
	v_and_b32_e32 v107, 0xffff0000, v102
	v_and_b32_e32 v106, 0xffff0000, v100
	v_lshlrev_b32_e32 v109, 16, v103
	v_and_b32_e32 v103, 0xffff0000, v103
	v_and_b32_e32 v102, 0xffff0000, v101
	v_lshlrev_b32_e32 v104, 16, v100
	v_lshlrev_b32_e32 v108, 16, v101
	v_pk_mul_f32 v[100:101], v[106:107], v[106:107]
	v_pk_mul_f32 v[110:111], v[102:103], v[102:103]
	v_pk_fma_f32 v[100:101], v[104:105], v[104:105], v[100:101]
	v_pk_fma_f32 v[110:111], v[108:109], v[108:109], v[110:111]
	v_lshlrev_b32_e32 v113, 16, v97
	v_pk_add_f32 v[100:101], v[100:101], v[110:111]
	v_lshlrev_b32_e32 v112, 16, v96
	v_and_b32_e32 v97, 0xffff0000, v97
	v_and_b32_e32 v96, 0xffff0000, v96
	v_pk_add_f32 v[100:101], v[100:101], v[100:101] op_sel_hi:[0,1]
	v_lshlrev_b32_e32 v110, 16, v98
	v_and_b32_e32 v111, 0xffff0000, v98
	v_pk_mul_f32 v[114:115], v[96:97], v[96:97]
	v_lshlrev_b32_e32 v98, 16, v99
	v_lshlrev_b32_e32 v116, 16, v88
	v_pk_fma_f32 v[114:115], v[112:113], v[112:113], v[114:115]
	v_mul_f32_e32 v117, v110, v110
	v_mul_f32_e32 v119, v111, v111
	v_and_b32_e32 v99, 0xffff0000, v99
	v_mul_f32_e32 v100, v98, v98
	v_mov_b32_e32 v118, v116
	v_pk_add_f32 v[114:115], v[114:115], v[114:115] op_sel_hi:[0,1]
	v_pk_fma_f32 v[136:137], v[98:99], v[98:99], v[100:101] op_sel_hi:[1,1,0]
	v_and_b32_e32 v135, 0xffff0000, v88
	v_lshlrev_b32_e32 v88, 16, v89
	v_and_b32_e32 v89, 0xffff0000, v89
	v_pk_add_f32 v[118:119], v[116:117], v[118:119]
	v_mul_f32_e32 v136, v135, v135
	v_mul_f32_e32 v100, v88, v88
	v_mul_f32_e32 v114, v89, v89
	v_mul_f32_e32 v138, v116, v116
	v_mov_b32_e32 v139, v119
	v_pk_add_f32 v[118:119], v[138:139], v[136:137]
	v_pk_add_f32 v[100:101], v[100:101], v[114:115]
	v_lshlrev_b32_e32 v115, 16, v91
	v_lshlrev_b32_e32 v114, 16, v90
	v_and_b32_e32 v91, 0xffff0000, v91
	v_and_b32_e32 v90, 0xffff0000, v90
	v_pk_add_f32 v[100:101], v[118:119], v[100:101]
	v_pk_mul_f32 v[118:119], v[90:91], v[90:91]
	v_lshlrev_b32_e32 v136, 16, v84
	v_and_b32_e32 v137, 0xffff0000, v84
	v_lshlrev_b32_e32 v138, 16, v86
	v_lshlrev_b32_e32 v142, 16, v85
	v_pk_fma_f32 v[118:119], v[114:115], v[114:115], v[118:119]
	v_and_b32_e32 v146, 0xffff0000, v86
	v_lshlrev_b32_e32 v140, 16, v87
	v_and_b32_e32 v141, 0xffff0000, v87
	v_mul_f32_e32 v139, v136, v136
	v_mul_f32_e32 v87, v137, v137
	v_and_b32_e32 v143, 0xffff0000, v85
	v_mul_f32_e32 v84, v142, v142
	v_mov_b32_e32 v86, v138
	v_pk_add_f32 v[100:101], v[100:101], v[100:101] op_sel_hi:[0,1]
	v_pk_add_f32 v[118:119], v[118:119], v[118:119] op_sel_hi:[0,1]
	v_pk_fma_f32 v[84:85], v[142:143], v[142:143], v[84:85] op_sel_hi:[1,1,0]
	v_pk_add_f32 v[86:87], v[138:139], v[86:87]
	v_mul_f32_e32 v84, v146, v146
	v_mul_f32_e32 v118, v140, v140
	v_mul_f32_e32 v100, v141, v141
	v_mul_f32_e32 v144, v138, v138
	v_mov_b32_e32 v145, v87
	v_pk_add_f32 v[84:85], v[144:145], v[84:85]
	v_pk_add_f32 v[86:87], v[118:119], v[100:101]
	v_lshl_add_u64 v[118:119], s[50:51], 0, v[2:3]
	v_pk_add_f32 v[84:85], v[84:85], v[86:87]
	v_mov_b32_e32 v117, v135
	v_add_f32_e32 v84, v84, v85
	v_mov_b32_e32 v139, v146
	s_nop 1
	v_add_f32_dpp v84, v84, v84 quad_perm:[1,0,3,2] row_mask:0xf bank_mask:0xf
	s_nop 1
	v_add_f32_dpp v84, v84, v84 quad_perm:[2,3,0,1] row_mask:0xf bank_mask:0xf
	s_nop 1
	v_add_f32_dpp v84, v84, v84 row_half_mirror row_mask:0xf bank_mask:0xf
	s_nop 1
	v_add_f32_dpp v84, v84, v84 row_mirror row_mask:0xf bank_mask:0xf
	v_mov_b32_e32 v85, v84
	s_nop 1
	v_permlane16_swap_b32_e32 v84, v85
	v_add_f32_e32 v84, v84, v85
	v_mov_b32_e32 v85, v84
	s_nop 1
	v_permlane32_swap_b32_e32 v84, v85
	s_waitcnt lgkmcnt(0)
	v_add_f32_e32 v84, v84, v85
	v_fmamk_f32 v84, v84, 0x3a000000, v234
	v_mul_f32_e32 v85, 0x4f800000, v84
	v_cmp_gt_f32_e32 vcc, s3, v84
	s_nop 1
	v_cndmask_b32_e32 v84, v84, v85, vcc
	v_sqrt_f32_e32 v85, v84
	s_nop 0
	v_add_u32_e32 v86, -1, v85
	v_fma_f32 v87, -v86, v85, v84
	v_cmp_ge_f32_e64 s[48:49], 0, v87
	v_add_u32_e32 v87, 1, v85
	s_nop 0
	v_cndmask_b32_e64 v86, v85, v86, s[48:49]
	v_fma_f32 v85, -v87, v85, v84
	v_cmp_lt_f32_e64 s[48:49], 0, v85
	s_nop 1
	v_cndmask_b32_e64 v85, v86, v87, s[48:49]
	v_mul_f32_e32 v86, 0x37800000, v85
	v_cndmask_b32_e32 v85, v85, v86, vcc
	v_cmp_class_f32_e32 vcc, v84, v235
	s_nop 1
	v_cndmask_b32_e32 v84, v85, v84, vcc
	v_div_scale_f32 v85, s[12:13], v84, v84, 1.0
	v_rcp_f32_e32 v86, v85
	s_nop 0
	v_fma_f32 v87, -v85, v86, 1.0
	v_fmac_f32_e32 v86, v87, v86
	v_div_scale_f32 v87, vcc, 1.0, v84, 1.0
	v_mul_f32_e32 v100, v87, v86
	v_fma_f32 v101, -v85, v100, v87
	v_fmac_f32_e32 v100, v101, v86
	v_fma_f32 v85, -v85, v100, v87
	v_div_fmas_f32 v85, v85, v86, v100
	v_div_fixup_f32 v100, v85, v84, 1.0
	v_mov_b32_e32 v84, v104
	v_mov_b32_e32 v85, v106
	v_mov_b32_e32 v86, v108
	v_mov_b32_e32 v87, v102
	v_mov_b32_e32 v102, v109
	v_pk_mul_f32 v[84:85], v[100:101], v[84:85] op_sel_hi:[0,1]
	v_pk_mul_f32 v[86:87], v[100:101], v[86:87] op_sel_hi:[0,1]
	v_mov_b32_e32 v106, v105
	v_pk_mul_f32 v[102:103], v[100:101], v[102:103] op_sel_hi:[0,1]
	v_pk_fma_f32 v[86:87], v[46:47], v[86:87], v[30:31]
	v_pk_fma_f32 v[84:85], v[44:45], v[84:85], v[28:29]
	v_pk_mul_f32 v[104:105], v[100:101], v[106:107] op_sel_hi:[0,1]
	v_pk_fma_f32 v[102:103], v[54:55], v[102:103], v[26:27]
	v_pk_fma_f32 v[104:105], v[52:53], v[104:105], v[24:25]
	v_cvt_pk_bf16_f32 v84, v84, v85
	v_cvt_pk_bf16_f32 v85, v86, v87
	v_cvt_pk_bf16_f32 v87, v102, v103
	v_add_co_u32_e32 v102, vcc, s24, v118
	v_cvt_pk_bf16_f32 v86, v104, v105
	s_nop 0
	v_addc_co_u32_e32 v103, vcc, 0, v119, vcc
	global_store_dwordx4 v[102:103], v[84:87], off
	v_pk_mul_f32 v[98:99], v[100:101], v[98:99] op_sel_hi:[0,1]
	v_pk_fma_f32 v[98:99], v[62:63], v[98:99], v[34:35]
	v_mov_b32_e32 v84, v112
	v_mov_b32_e32 v85, v96
	v_mov_b32_e32 v96, v113
	v_pk_mul_f32 v[84:85], v[100:101], v[84:85] op_sel_hi:[0,1]
	v_pk_mul_f32 v[86:87], v[100:101], v[96:97] op_sel_hi:[0,1]
	v_pk_mul_f32 v[96:97], v[100:101], v[110:111] op_sel_hi:[0,1]
	v_pk_fma_f32 v[86:87], v[58:59], v[86:87], v[38:39]
	v_pk_fma_f32 v[84:85], v[56:57], v[84:85], v[36:37]
	v_pk_fma_f32 v[96:97], v[60:61], v[96:97], v[32:33]
	v_cvt_pk_bf16_f32 v84, v84, v85
	v_cvt_pk_bf16_f32 v85, v86, v87
	v_cvt_pk_bf16_f32 v86, v96, v97
	v_cvt_pk_bf16_f32 v87, v98, v99
	global_store_dwordx4 v[102:103], v[84:87], off offset:1024
	s_nop 1
	v_pk_mul_f32 v[86:87], v[100:101], v[88:89] op_sel_hi:[0,1]
	v_mov_b32_e32 v88, v114
	v_mov_b32_e32 v89, v90
	v_mov_b32_e32 v90, v115
	v_pk_mul_f32 v[84:85], v[100:101], v[116:117] op_sel_hi:[0,1]
	v_pk_mul_f32 v[88:89], v[100:101], v[88:89] op_sel_hi:[0,1]
	v_pk_mul_f32 v[90:91], v[100:101], v[90:91] op_sel_hi:[0,1]
	v_pk_fma_f32 v[86:87], v[66:67], v[86:87], v[50:51]
	v_pk_fma_f32 v[84:85], v[64:65], v[84:85], v[48:49]
	v_pk_fma_f32 v[90:91], v[70:71], v[90:91], v[42:43]
	v_pk_fma_f32 v[88:89], v[68:69], v[88:89], v[40:41]
	v_cvt_pk_bf16_f32 v84, v84, v85
	v_cvt_pk_bf16_f32 v85, v86, v87
	v_cvt_pk_bf16_f32 v86, v88, v89
	v_cvt_pk_bf16_f32 v87, v90, v91
	global_store_dwordx4 v[102:103], v[84:87], off offset:2048
	v_pk_mul_f32 v[88:89], v[100:101], v[138:139] op_sel_hi:[0,1]
	v_pk_mul_f32 v[90:91], v[100:101], v[140:141] op_sel_hi:[0,1]
	v_pk_mul_f32 v[84:85], v[100:101], v[136:137] op_sel_hi:[0,1]
	v_pk_mul_f32 v[86:87], v[100:101], v[142:143] op_sel_hi:[0,1]
	s_waitcnt vmcnt(3)
	v_pk_fma_f32 v[86:87], v[82:83], v[86:87], v[78:79]
	v_pk_fma_f32 v[84:85], v[80:81], v[84:85], v[76:77]
	v_pk_fma_f32 v[90:91], v[94:95], v[90:91], v[74:75]
	v_pk_fma_f32 v[88:89], v[92:93], v[88:89], v[72:73]
	v_cvt_pk_bf16_f32 v84, v84, v85
	v_cvt_pk_bf16_f32 v85, v86, v87
	v_cvt_pk_bf16_f32 v86, v88, v89
	v_cvt_pk_bf16_f32 v87, v90, v91
	global_store_dwordx4 v[102:103], v[84:87], off offset:3072

.LBB0_462:
	s_lshl_b32 s90, s21, 1
	s_nop 0
	v_lshl_add_u64 v[18:19], v[60:61], 0, s[90:91]
	global_store_short v[18:19], v116, off
	global_store_short_d16_hi v[18:19], v116, off offset:512
	global_store_short v[18:19], v117, off offset:1024
	global_store_short_d16_hi v[18:19], v117, off offset:1536
	s_nop 0
	s_lshl_b64 s[12:13], s[8:9], 10
	v_lshlrev_b32_e32 v84, 16, v120
	v_and_b32_e32 v85, 0xffff0000, v120
	v_lshlrev_b32_e32 v80, 16, v123
	v_and_b32_e32 v81, 0xffff0000, v123
	v_lshlrev_b32_e32 v82, 16, v122
	v_and_b32_e32 v83, 0xffff0000, v122
	v_lshlrev_b32_e32 v18, 16, v121
	v_and_b32_e32 v19, 0xffff0000, v121
	v_pk_mul_f32 v[90:91], v[84:85], v[84:85]
	v_pk_mul_f32 v[88:89], v[18:19], v[18:19]
	v_add_f32_e32 v2, v90, v91
	v_add_f32_e32 v2, v88, v2
	v_pk_mul_f32 v[86:87], v[82:83], v[82:83]
	v_add_f32_e32 v2, v89, v2
	v_add_f32_e32 v2, v86, v2
	v_pk_mul_f32 v[16:17], v[80:81], v[80:81]
	v_add_f32_e32 v2, v87, v2
	v_add_f32_e32 v2, v16, v2
	v_add_f32_e32 v2, v17, v2
	v_lshl_add_u64 v[86:87], v[38:39], 0, s[12:13]
	s_nop 1
	v_add_f32_dpp v2, v2, v2 quad_perm:[1,0,3,2] row_mask:0xf bank_mask:0xf
	s_nop 1
	v_add_f32_dpp v2, v2, v2 quad_perm:[2,3,0,1] row_mask:0xf bank_mask:0xf
	s_nop 1
	v_add_f32_dpp v2, v2, v2 row_half_mirror row_mask:0xf bank_mask:0xf
	s_nop 1
	v_add_f32_dpp v2, v2, v2 row_mirror row_mask:0xf bank_mask:0xf
	v_mov_b32_e32 v5, v2
	s_nop 1
	v_permlane16_swap_b32_e32 v2, v5
	v_add_f32_e32 v2, v2, v5
	v_mov_b32_e32 v16, v2
	s_nop 1
	v_permlane32_swap_b32_e32 v2, v16
	v_mov_b32_e32 v5, v3
	s_waitcnt lgkmcnt(0)
	v_add_f32_e32 v2, v2, v16
	v_fmamk_f32 v2, v2, 0x3b000000, v234
	v_mul_f32_e32 v16, 0x4f800000, v2
	v_cmp_gt_f32_e32 vcc, s3, v2
	s_nop 1
	v_cndmask_b32_e32 v2, v2, v16, vcc
	v_sqrt_f32_e32 v57, v2
	v_lshl_add_u64 v[16:17], s[10:11], 0, v[4:5]
	v_add_u32_e32 v5, -1, v57
	v_add_u32_e32 v59, 1, v57
	v_fma_f32 v75, -v5, v57, v2
	v_fma_f32 v88, -v59, v57, v2
	v_cmp_ge_f32_e64 s[62:63], 0, v75
	s_nop 1
	v_cndmask_b32_e64 v5, v57, v5, s[62:63]
	v_cmp_lt_f32_e64 s[62:63], 0, v88
	s_nop 1
	v_cndmask_b32_e64 v5, v5, v59, s[62:63]
	v_mul_f32_e32 v57, 0x37800000, v5
	v_cndmask_b32_e32 v5, v5, v57, vcc
	v_cmp_class_f32_e32 vcc, v2, v235
	s_nop 1
	v_cndmask_b32_e32 v2, v5, v2, vcc
	v_div_scale_f32 v5, s[16:17], v2, v2, 1.0
	v_rcp_f32_e32 v57, v5
	v_add_co_u32_e32 v88, vcc, s28, v16
	s_nop 1
	v_addc_co_u32_e32 v89, vcc, 0, v17, vcc
	v_fma_f32 v17, -v5, v57, 1.0
	v_div_scale_f32 v16, vcc, 1.0, v2, 1.0
	v_fmac_f32_e32 v57, v17, v57
	v_mul_f32_e32 v17, v16, v57
	v_fma_f32 v59, -v5, v17, v16
	v_fmac_f32_e32 v17, v59, v57
	v_fma_f32 v5, -v5, v17, v16
	v_div_fmas_f32 v5, v5, v57, v17
	v_div_fixup_f32 v2, v5, v2, 1.0
	v_pk_mul_f32 v[16:17], v[128:129], v[2:3] op_sel_hi:[1,0]
	v_pk_mul_f32 v[76:77], v[130:131], v[2:3] op_sel_hi:[1,0]
	v_pk_mul_f32 v[20:21], v[124:125], v[2:3] op_sel_hi:[1,0]
	v_pk_mul_f32 v[22:23], v[126:127], v[2:3] op_sel_hi:[1,0]
	v_pk_mul_f32 v[16:17], v[16:17], v[84:85]
	v_pk_mul_f32 v[18:19], v[76:77], v[18:19]
	v_pk_mul_f32 v[20:21], v[20:21], v[82:83]
	v_pk_mul_f32 v[22:23], v[22:23], v[80:81]
	v_cvt_pk_bf16_f32 v16, v16, v17
	v_cvt_pk_bf16_f32 v17, v18, v19
	v_cvt_pk_bf16_f32 v18, v20, v21
	v_cvt_pk_bf16_f32 v19, v22, v23
	global_store_dwordx4 v[86:87], v[16:19], off
	s_nop 0
	v_lshlrev_b32_e32 v80, 16, v132
	v_and_b32_e32 v81, 0xffff0000, v132
	v_lshlrev_b32_e32 v16, 16, v133
	v_and_b32_e32 v17, 0xffff0000, v133
	v_pk_mul_f32 v[84:85], v[80:81], v[80:81]
	v_pk_mul_f32 v[86:87], v[16:17], v[16:17]
	v_add_f32_e32 v2, v84, v85
	v_lshlrev_b32_e32 v82, 16, v134
	v_and_b32_e32 v83, 0xffff0000, v134
	v_add_f32_e32 v2, v86, v2
	v_pk_mul_f32 v[88:89], v[82:83], v[82:83]
	v_add_f32_e32 v2, v87, v2
	v_lshlrev_b32_e32 v18, 16, v135
	v_and_b32_e32 v19, 0xffff0000, v135
	v_add_f32_e32 v2, v88, v2
	v_pk_mul_f32 v[90:91], v[18:19], v[18:19]
	v_add_f32_e32 v2, v89, v2
	v_add_f32_e32 v2, v90, v2
	v_add_f32_e32 v2, v91, v2
	s_nop 1
	v_add_f32_dpp v2, v2, v2 quad_perm:[1,0,3,2] row_mask:0xf bank_mask:0xf
	s_nop 1
	v_add_f32_dpp v2, v2, v2 quad_perm:[2,3,0,1] row_mask:0xf bank_mask:0xf
	s_nop 1
	v_add_f32_dpp v2, v2, v2 row_half_mirror row_mask:0xf bank_mask:0xf
	s_nop 1
	v_add_f32_dpp v2, v2, v2 row_mirror row_mask:0xf bank_mask:0xf
	v_mov_b32_e32 v5, v2
	s_nop 1
	v_permlane16_swap_b32_e32 v2, v5
	v_add_f32_e32 v2, v2, v5
	v_mov_b32_e32 v5, v2
	s_nop 1
	v_permlane32_swap_b32_e32 v2, v5
	s_waitcnt lgkmcnt(0)
	v_add_f32_e32 v2, v2, v5
	v_fmamk_f32 v2, v2, 0x3b000000, v234
	v_mul_f32_e32 v5, 0x4f800000, v2
	v_cmp_gt_f32_e32 vcc, s3, v2
	s_nop 1
	v_cndmask_b32_e32 v2, v2, v5, vcc
	v_sqrt_f32_e32 v5, v2
	s_nop 0
	v_add_u32_e32 v57, -1, v5
	v_add_u32_e32 v59, 1, v5
	v_fma_f32 v75, -v57, v5, v2
	v_fma_f32 v84, -v59, v5, v2
	v_cmp_ge_f32_e64 s[62:63], 0, v75
	s_nop 1
	v_cndmask_b32_e64 v5, v5, v57, s[62:63]
	v_cmp_lt_f32_e64 s[62:63], 0, v84
	v_lshl_add_u64 v[84:85], v[42:43], 0, s[12:13]
	s_nop 0
	v_cndmask_b32_e64 v5, v5, v59, s[62:63]
	v_mul_f32_e32 v57, 0x37800000, v5
	v_cndmask_b32_e32 v5, v5, v57, vcc
	v_cmp_class_f32_e32 vcc, v2, v235
	s_nop 1
	v_cndmask_b32_e32 v2, v5, v2, vcc
	v_div_scale_f32 v5, s[16:17], v2, v2, 1.0
	v_rcp_f32_e32 v57, v5
	v_div_scale_f32 v59, vcc, 1.0, v2, 1.0
	v_fma_f32 v75, -v5, v57, 1.0
	v_fmac_f32_e32 v57, v75, v57
	v_mul_f32_e32 v75, v59, v57
	v_fma_f32 v86, -v5, v75, v59
	v_fmac_f32_e32 v75, v86, v57
	v_fma_f32 v5, -v5, v75, v59
	v_div_fmas_f32 v5, v5, v57, v75
	v_div_fixup_f32 v2, v5, v2, 1.0
	v_pk_mul_f32 v[76:77], v[140:141], v[2:3] op_sel_hi:[1,0]
	v_pk_mul_f32 v[78:79], v[142:143], v[2:3] op_sel_hi:[1,0]
	v_pk_mul_f32 v[86:87], v[136:137], v[2:3] op_sel_hi:[1,0]
	v_pk_mul_f32 v[88:89], v[138:139], v[2:3] op_sel_hi:[1,0]
	v_pk_mul_f32 v[20:21], v[76:77], v[80:81]
	v_pk_mul_f32 v[22:23], v[78:79], v[16:17]
	v_pk_mul_f32 v[16:17], v[86:87], v[82:83]
	v_pk_mul_f32 v[18:19], v[88:89], v[18:19]
	v_cvt_pk_bf16_f32 v76, v20, v21
	v_cvt_pk_bf16_f32 v77, v22, v23
	v_cvt_pk_bf16_f32 v78, v16, v17
	v_cvt_pk_bf16_f32 v79, v18, v19
	s_and_b64 vcc, exec, s[60:61]
	global_store_dwordx4 v[84:85], v[76:79], off
	s_cbranch_vccnz .LBB0_464
	s_lshl_b32 s90, s21, 11
	v_lshl_add_u64 v[76:77], v[66:67], 0, s[90:91]
	global_store_dwordx4 v[76:77], v[20:23], off
	global_store_dwordx4 v[76:77], v[16:19], off offset:16

.LBB0_1544:
	global_load_dwordx4 v[44:47], v[48:49], off
	global_load_dwordx4 v[40:43], v[48:49], off offset:1024
	global_load_dwordx4 v[36:39], v[48:49], off offset:2048
	global_load_dwordx4 v[32:35], v[48:49], off offset:3072
	s_add_i32 s2, s2, s94
	v_lshl_add_u64 v[48:49], v[48:49], 0, s[4:5]
	s_cmpk_lt_i32 s2, 0x3000
	s_waitcnt vmcnt(0)
	v_lshlrev_b32_e32 v61, 16, v46
	v_and_b32_e32 v63, 0xffff0000, v46
	v_and_b32_e32 v62, 0xffff0000, v44
	v_lshlrev_b32_e32 v65, 16, v47
	v_and_b32_e32 v47, 0xffff0000, v47
	v_and_b32_e32 v46, 0xffff0000, v45
	v_lshlrev_b32_e32 v60, 16, v44
	v_lshlrev_b32_e32 v64, 16, v45
	v_lshlrev_b32_e32 v67, 16, v41
	v_lshlrev_b32_e32 v66, 16, v40
	v_and_b32_e32 v41, 0xffff0000, v41
	v_and_b32_e32 v40, 0xffff0000, v40
	v_pk_mul_f32 v[76:77], v[62:63], v[62:63]
	v_pk_mul_f32 v[78:79], v[46:47], v[46:47]
	v_lshlrev_b32_e32 v44, 16, v42
	v_and_b32_e32 v45, 0xffff0000, v42
	v_lshlrev_b32_e32 v42, 16, v43
	v_lshlrev_b32_e32 v68, 16, v36
	v_pk_mul_f32 v[80:81], v[40:41], v[40:41]
	v_mov_b32_e32 v96, v60
	v_mov_b32_e32 v97, v62
	v_mov_b32_e32 v98, v64
	v_mov_b32_e32 v99, v46
	v_mov_b32_e32 v62, v61
	v_mov_b32_e32 v46, v65
	v_pk_fma_f32 v[60:61], v[60:61], v[60:61], v[76:77]
	v_pk_fma_f32 v[64:65], v[64:65], v[64:65], v[78:79]
	v_and_b32_e32 v43, 0xffff0000, v43
	v_and_b32_e32 v85, 0xffff0000, v36
	v_lshlrev_b32_e32 v71, 16, v39
	v_lshlrev_b32_e32 v70, 16, v38
	v_and_b32_e32 v39, 0xffff0000, v39
	v_and_b32_e32 v38, 0xffff0000, v38
	v_mul_f32_e32 v69, v44, v44
	v_mul_f32_e32 v83, v45, v45
	v_mul_f32_e32 v84, v42, v42
	v_mov_b32_e32 v82, v68
	v_mov_b32_e32 v100, v66
	v_mov_b32_e32 v101, v40
	v_mov_b32_e32 v40, v67
	v_pk_fma_f32 v[66:67], v[66:67], v[66:67], v[80:81]
	v_pk_add_f32 v[60:61], v[60:61], v[64:65]
	v_lshlrev_b32_e32 v36, 16, v37
	v_and_b32_e32 v37, 0xffff0000, v37
	v_pk_mul_f32 v[88:89], v[38:39], v[38:39]
	v_pk_fma_f32 v[76:77], v[42:43], v[42:43], v[84:85] op_sel_hi:[1,1,0]
	v_pk_add_f32 v[78:79], v[68:69], v[82:83]
	v_pk_add_f32 v[64:65], v[66:67], v[66:67] op_sel_hi:[0,1]
	v_pk_add_f32 v[60:61], v[60:61], v[60:61] op_sel_hi:[0,1]
	v_mul_f32_e32 v86, v68, v68
	v_mov_b32_e32 v102, v70
	v_mov_b32_e32 v103, v38
	v_mov_b32_e32 v38, v71
	v_pk_fma_f32 v[70:71], v[70:71], v[70:71], v[88:89]
	v_mul_f32_e32 v76, v85, v85
	v_mov_b32_e32 v87, v79
	v_mul_f32_e32 v64, v37, v37
	v_mul_f32_e32 v60, v36, v36
	v_lshlrev_b32_e32 v72, 16, v32
	v_and_b32_e32 v73, 0xffff0000, v32
	v_lshlrev_b32_e32 v32, 16, v34
	v_lshlrev_b32_e32 v74, 16, v33
	v_pk_add_f32 v[66:67], v[70:71], v[70:71] op_sel_hi:[0,1]
	v_pk_add_f32 v[70:71], v[86:87], v[76:77]
	v_pk_add_f32 v[60:61], v[60:61], v[64:65]
	v_and_b32_e32 v93, 0xffff0000, v34
	v_and_b32_e32 v75, 0xffff0000, v33
	v_mul_f32_e32 v33, v72, v72
	v_mul_f32_e32 v91, v73, v73
	v_mul_f32_e32 v92, v74, v74
	v_mov_b32_e32 v90, v32
	v_pk_add_f32 v[60:61], v[70:71], v[60:61]
	v_lshlrev_b32_e32 v34, 16, v35
	v_and_b32_e32 v35, 0xffff0000, v35
	v_pk_fma_f32 v[80:81], v[74:75], v[74:75], v[92:93] op_sel_hi:[1,1,0]
	v_pk_add_f32 v[82:83], v[32:33], v[90:91]
	v_pk_add_f32 v[60:61], v[60:61], v[60:61] op_sel_hi:[0,1]
	v_mul_f32_e32 v94, v32, v32
	v_mul_f32_e32 v80, v93, v93
	v_mov_b32_e32 v95, v83
	v_mul_f32_e32 v66, v34, v34
	v_mul_f32_e32 v60, v35, v35
	v_pk_add_f32 v[76:77], v[94:95], v[80:81]
	v_pk_add_f32 v[60:61], v[66:67], v[60:61]
	v_mov_b32_e32 v69, v85
	v_pk_add_f32 v[60:61], v[76:77], v[60:61]
	v_mov_b32_e32 v33, v93
	v_add_f32_e32 v60, v60, v61
	s_nop 1
	v_add_f32_dpp v60, v60, v60 quad_perm:[1,0,3,2] row_mask:0xf bank_mask:0xf
	s_nop 1
	v_add_f32_dpp v60, v60, v60 quad_perm:[2,3,0,1] row_mask:0xf bank_mask:0xf
	s_nop 1
	v_add_f32_dpp v60, v60, v60 row_half_mirror row_mask:0xf bank_mask:0xf
	s_nop 1
	v_add_f32_dpp v60, v60, v60 row_mirror row_mask:0xf bank_mask:0xf
	v_mov_b32_e32 v61, v60
	s_nop 1
	v_permlane16_swap_b32_e32 v60, v61
	v_add_f32_e32 v60, v60, v61
	v_mov_b32_e32 v61, v60
	s_nop 1
	v_permlane32_swap_b32_e32 v60, v61
	s_waitcnt lgkmcnt(0)
	v_add_f32_e32 v60, v60, v61
	v_fmamk_f32 v60, v60, 0x3a000000, v58
	v_mul_f32_e32 v61, 0x4f800000, v60
	v_cmp_gt_f32_e32 vcc, s3, v60
	s_nop 1
	v_cndmask_b32_e32 v60, v60, v61, vcc
	v_sqrt_f32_e32 v61, v60
	s_nop 0
	v_add_u32_e32 v64, -1, v61
	v_add_u32_e32 v65, 1, v61
	v_fma_f32 v66, -v64, v61, v60
	v_fma_f32 v67, -v65, v61, v60
	v_cmp_ge_f32_e64 s[0:1], 0, v66
	s_nop 1
	v_cndmask_b32_e64 v61, v61, v64, s[0:1]
	v_cmp_lt_f32_e64 s[0:1], 0, v67
	s_nop 1
	v_cndmask_b32_e64 v61, v61, v65, s[0:1]
	v_mul_f32_e32 v64, 0x37800000, v61
	v_cndmask_b32_e32 v61, v61, v64, vcc
	v_cmp_class_f32_e32 vcc, v60, v59
	s_nop 1
	v_cndmask_b32_e32 v60, v61, v60, vcc
	v_div_scale_f32 v61, s[0:1], v60, v60, 1.0
	v_rcp_f32_e32 v65, v61
	v_div_scale_f32 v64, vcc, 1.0, v60, 1.0
	v_fma_f32 v66, -v61, v65, 1.0
	v_fmac_f32_e32 v65, v66, v65
	v_mul_f32_e32 v66, v64, v65
	v_fma_f32 v67, -v61, v66, v64
	v_fmac_f32_e32 v66, v67, v65
	v_fma_f32 v61, -v61, v66, v64
	v_div_fmas_f32 v61, v61, v65, v66
	v_div_fixup_f32 v60, v61, v60, 1.0
	v_pk_mul_f32 v[64:65], v[60:61], v[96:97] op_sel_hi:[0,1]
	v_pk_mul_f32 v[66:67], v[60:61], v[98:99] op_sel_hi:[0,1]
	v_pk_mul_f32 v[62:63], v[60:61], v[62:63] op_sel_hi:[0,1]
	v_pk_mul_f32 v[46:47], v[60:61], v[46:47] op_sel_hi:[0,1]
	v_pk_mul_f32 v[70:71], v[60:61], v[100:101] op_sel_hi:[0,1]
	v_pk_mul_f32 v[40:41], v[60:61], v[40:41] op_sel_hi:[0,1]
	v_pk_mul_f32 v[44:45], v[60:61], v[44:45] op_sel_hi:[0,1]
	v_pk_mul_f32 v[76:77], v[60:61], v[42:43] op_sel_hi:[0,1]
	v_pk_mul_f32 v[68:69], v[60:61], v[68:69] op_sel_hi:[0,1]
	v_pk_mul_f32 v[78:79], v[60:61], v[36:37] op_sel_hi:[0,1]
	v_pk_mul_f32 v[80:81], v[60:61], v[102:103] op_sel_hi:[0,1]
	v_pk_mul_f32 v[82:83], v[60:61], v[38:39] op_sel_hi:[0,1]
	v_pk_mul_f32 v[72:73], v[60:61], v[72:73] op_sel_hi:[0,1]
	v_pk_mul_f32 v[74:75], v[60:61], v[74:75] op_sel_hi:[0,1]
	v_pk_mul_f32 v[84:85], v[60:61], v[32:33] op_sel_hi:[0,1]
	v_pk_mul_f32 v[86:87], v[60:61], v[34:35] op_sel_hi:[0,1]
	v_pk_mul_f32 v[34:35], v[6:7], v[66:67]
	v_pk_mul_f32 v[32:33], v[4:5], v[64:65]
	v_pk_mul_f32 v[38:39], v[2:3], v[46:47]
	v_pk_mul_f32 v[36:37], v[0:1], v[62:63]
	v_pk_mul_f32 v[42:43], v[14:15], v[40:41]
	v_pk_mul_f32 v[40:41], v[12:13], v[70:71]
	v_pk_mul_f32 v[46:47], v[10:11], v[76:77]
	v_pk_mul_f32 v[44:45], v[8:9], v[44:45]
	v_pk_mul_f32 v[62:63], v[18:19], v[78:79]
	v_pk_mul_f32 v[60:61], v[16:17], v[68:69]
	v_pk_mul_f32 v[66:67], v[22:23], v[82:83]
	v_pk_mul_f32 v[64:65], v[20:21], v[80:81]
	v_pk_mul_f32 v[70:71], v[26:27], v[74:75]
	v_pk_mul_f32 v[68:69], v[24:25], v[72:73]
	v_pk_mul_f32 v[74:75], v[30:31], v[86:87]
	v_pk_mul_f32 v[72:73], v[28:29], v[84:85]
	global_store_dwordx4 v[50:51], v[32:35], off offset:-4096
	global_store_dwordx4 v[50:51], v[36:39], off offset:-4080
	global_store_dwordx4 v[50:51], v[40:43], off offset:-2048
	global_store_dwordx4 v[50:51], v[44:47], off offset:-2032
	global_store_dwordx4 v[50:51], v[60:63], off
	global_store_dwordx4 v[50:51], v[64:67], off offset:16
	global_store_dwordx4 v[50:51], v[68:71], off offset:2048
	global_store_dwordx4 v[50:51], v[72:75], off offset:2064
	v_lshl_add_u64 v[50:51], v[50:51], 0, s[6:7]
	s_cbranch_scc1 .LBB0_1544
